# RG-LRU pass-3 carry-in as a scalar slot walk (valid slots are a prefix per wave): 34 loads in flight, no exec masking, no mid-way drain
# speedup vs baseline: 1.1078x; 1.0027x over previous
; DI float bf2f(u16 v) { return __uint_as_float(((unsigned)v) << 16); }
;     ...
;   __syncthreads();
;   {
;     const int c = tid & 63, tq = tid >> 6, cg = g * 64 + c;
;     const float w0 = p->lru_conv_w[(l * 4 + 0) * 512 + cg], w1 = p->lru_conv_w[(l * 4 + 1) * 512 + cg];
;     const float w2 = p->lru_conv_w[(l * 4 + 2) * 512 + cg], w3 = p->lru_conv_w[(l * 4 + 3) * 512 + cg];
;     const float bias = p->lru_conv_b[l * 512 + cg];
;     auto ld = [&](int tt) -> float {
;       int tp = tpos0 + tt;
;       return (tp >= 0 && tp < seglen) ? bf2f(Zlx[(size_t)(base + tt) * 512 + cg]) : 0.f;
;     };
;     const int t0 = tq * 16;
;     float xv[19];
; #pragma unroll
;     for (int e = 0; e < 19; ++e) xv[e] = ld(t0 - 2 + e);
; #pragma unroll
;     for (int tt = 0; tt < 16; ++tt) {
;       const float y = w0 * xv[tt] + w1 * xv[tt + 1] + w2 * xv[tt + 2] + w3 * xv[tt + 3] + bias;
;       uf[(t0 + tt) * 65 + c] = y;
;       Au[(t0 + tt) * 72 + c] = f2bf(y);
;     }
.LBB0_1168:
	s_load_dwordx2 s[6:7], s[16:17], 0x130
	s_waitcnt lgkmcnt(0)
	s_barrier
	s_load_dwordx4 s[8:11], s[16:17], 0x68
	s_and_b32 s29, s5, 7
	v_and_b32_e32 v77, 63, v76
	s_lshl_b32 s28, s29, 6
	v_or_b32_e32 v4, s28, v77
	s_waitcnt lgkmcnt(0)
	v_mov_b32_e32 v2, s8
	v_mov_b32_e32 v3, s9
	v_or_b32_e32 v198, s77, v4
	v_lshl_add_u64 v[2:3], v[198:199], 2, v[2:3]
	v_add_co_u32_e32 v12, vcc, s47, v2
	v_mov_b32_e32 v10, s10
	v_mov_b32_e32 v11, s11
	v_addc_co_u32_e32 v13, vcc, 0, v3, vcc
	global_load_dword v5, v[2:3], off
	global_load_dword v8, v[2:3], off offset:2048
	global_load_dword v7, v[12:13], off
	global_load_dword v6, v[12:13], off offset:2048
	v_or_b32_e32 v198, s80, v4
	v_lshl_add_u64 v[2:3], v[198:199], 2, v[10:11]
	global_load_dword v9, v[2:3], off
	v_ashrrev_i32_e32 v10, 6, v76
	v_lshlrev_b32_e32 v14, 4, v10
	v_lshlrev_b32_e32 v31, 1, v4
	v_add_u32_e32 v38, s27, v14
	s_add_u32 s8, s6, 0x3850000
	s_addc_u32 s9, s7, 0
	v_lshl_add_u32 v31, v38, 10, v31
	v_add_u32_e32 v34, 0x1000, v31
	v_add_u32_e32 v35, 0x2000, v31
	v_add_u32_e32 v36, 0x3000, v31
	v_add_u32_e32 v37, 0x4000, v31
	global_load_ushort v12, v31, s[8:9] offset:-2048
	global_load_ushort v11, v31, s[8:9] offset:-1024
	global_load_ushort v15, v31, s[8:9]
	global_load_ushort v13, v31, s[8:9] offset:1024
	global_load_ushort v18, v31, s[8:9] offset:2048
	global_load_ushort v16, v31, s[8:9] offset:3072
	global_load_ushort v20, v34, s[8:9]
	global_load_ushort v19, v34, s[8:9] offset:1024
	global_load_ushort v22, v34, s[8:9] offset:2048
	global_load_ushort v21, v34, s[8:9] offset:3072
	global_load_ushort v24, v35, s[8:9]
	global_load_ushort v23, v35, s[8:9] offset:1024
	global_load_ushort v26, v35, s[8:9] offset:2048
	global_load_ushort v25, v35, s[8:9] offset:3072
	global_load_ushort v28, v36, s[8:9]
	global_load_ushort v27, v36, s[8:9] offset:1024
	global_load_ushort v30, v36, s[8:9] offset:2048
	global_load_ushort v29, v36, s[8:9] offset:3072
	global_load_ushort v39, v37, s[8:9]
	v_or_b32_e32 v17, 1, v14
	v_add_u32_e32 v38, s3, v14
	v_add_u32_e32 v40, -2, v38
	s_waitcnt vmcnt(0)
	v_cmp_gt_u32_e32 vcc, s4, v40
	v_lshlrev_b32_e32 v12, 16, v12
	v_add_u32_e32 v41, -1, v38
	v_cndmask_b32_e32 v12, 0, v12, vcc
	v_cmp_gt_u32_e32 vcc, s4, v41
	v_lshlrev_b32_e32 v11, 16, v11
	v_add_u32_e32 v40, 0, v38
	v_cndmask_b32_e32 v11, 0, v11, vcc
	v_cmp_gt_u32_e32 vcc, s4, v40
	v_lshlrev_b32_e32 v15, 16, v15
	v_add_u32_e32 v41, 1, v38
	v_cndmask_b32_e32 v15, 0, v15, vcc
	v_cmp_gt_u32_e32 vcc, s4, v41
	v_lshlrev_b32_e32 v13, 16, v13
	v_add_u32_e32 v40, 2, v38
	v_cndmask_b32_e32 v13, 0, v13, vcc
	v_cmp_gt_u32_e32 vcc, s4, v40
	v_lshlrev_b32_e32 v18, 16, v18
	v_add_u32_e32 v41, 3, v38
	v_cndmask_b32_e32 v18, 0, v18, vcc
	v_cmp_gt_u32_e32 vcc, s4, v41
	v_lshlrev_b32_e32 v16, 16, v16
	v_add_u32_e32 v40, 4, v38
	v_cndmask_b32_e32 v16, 0, v16, vcc
	v_cmp_gt_u32_e32 vcc, s4, v40
	v_lshlrev_b32_e32 v20, 16, v20
	v_add_u32_e32 v41, 5, v38
	v_cndmask_b32_e32 v20, 0, v20, vcc
	v_cmp_gt_u32_e32 vcc, s4, v41
	v_lshlrev_b32_e32 v19, 16, v19
	v_add_u32_e32 v40, 6, v38
	v_cndmask_b32_e32 v19, 0, v19, vcc
	v_cmp_gt_u32_e32 vcc, s4, v40
	v_lshlrev_b32_e32 v22, 16, v22
	v_add_u32_e32 v41, 7, v38
	v_cndmask_b32_e32 v22, 0, v22, vcc
	v_cmp_gt_u32_e32 vcc, s4, v41
	v_lshlrev_b32_e32 v21, 16, v21
	v_add_u32_e32 v40, 8, v38
	v_cndmask_b32_e32 v21, 0, v21, vcc
	v_cmp_gt_u32_e32 vcc, s4, v40
	v_lshlrev_b32_e32 v24, 16, v24
	v_add_u32_e32 v41, 9, v38
	v_cndmask_b32_e32 v24, 0, v24, vcc
	v_cmp_gt_u32_e32 vcc, s4, v41
	v_lshlrev_b32_e32 v23, 16, v23
	v_add_u32_e32 v40, 10, v38
	v_cndmask_b32_e32 v23, 0, v23, vcc
	v_cmp_gt_u32_e32 vcc, s4, v40
	v_lshlrev_b32_e32 v26, 16, v26
	v_add_u32_e32 v41, 11, v38
	v_cndmask_b32_e32 v26, 0, v26, vcc
	v_cmp_gt_u32_e32 vcc, s4, v41
	v_lshlrev_b32_e32 v25, 16, v25
	v_add_u32_e32 v40, 12, v38
	v_cndmask_b32_e32 v25, 0, v25, vcc
	v_cmp_gt_u32_e32 vcc, s4, v40
	v_lshlrev_b32_e32 v28, 16, v28
	v_add_u32_e32 v41, 13, v38
	v_cndmask_b32_e32 v28, 0, v28, vcc
	v_cmp_gt_u32_e32 vcc, s4, v41
	v_lshlrev_b32_e32 v27, 16, v27
	v_add_u32_e32 v40, 14, v38
	v_cndmask_b32_e32 v27, 0, v27, vcc
	v_cmp_gt_u32_e32 vcc, s4, v40
	v_lshlrev_b32_e32 v30, 16, v30
	v_add_u32_e32 v41, 15, v38
	v_cndmask_b32_e32 v30, 0, v30, vcc
	v_cmp_gt_u32_e32 vcc, s4, v41
	v_lshlrev_b32_e32 v29, 16, v29
	v_add_u32_e32 v40, 16, v38
	v_cndmask_b32_e32 v29, 0, v29, vcc
	v_cmp_gt_u32_e32 vcc, s4, v40
	v_lshlrev_b32_e32 v39, 16, v39
	s_nop 0
	v_cndmask_b32_e32 v39, 0, v39, vcc
	v_mov_b32_e32 v14, v39
	v_lshlrev_b32_e32 v2, 2, v77
	v_lshlrev_b32_e32 v3, 1, v77
	v_sub_u32_e32 v32, v2, v3
	s_waitcnt vmcnt(3)
	v_mul_f32_e32 v3, v8, v11
	v_fmac_f32_e32 v3, v5, v12
	s_waitcnt vmcnt(2)
	v_fmac_f32_e32 v3, v7, v15
	s_waitcnt vmcnt(1)
	v_fmac_f32_e32 v3, v6, v13
	s_waitcnt vmcnt(0)
;     ...
; #pragma unroll
;     for (int tt = 0; tt < 16; ++tt) {
;       const float y = w0 * xv[tt] + w1 * xv[tt + 1] + w2 * xv[tt + 2] + w3 * xv[tt + 3] + bias;
;       uf[(t0 + tt) * 65 + c] = y;
;       Au[(t0 + tt) * 72 + c] = f2bf(y);
;     }
;   }
;   if (pass == 3) {
;     const int part = tid >> 7, dir = (tid >> 6) & 1, c = tid & 63, cg = g * 64 + c;
;     const f32x2* ag = agg + ((size_t)(b * 68) * 2 + dir) * 512 + cg;
;     f32x2 ab[34];
; #pragma unroll
;     for (int e = 0; e < 34; ++e) {
;       const int sl = part * 34 + e;
;       int ch; bool valid;
;       if (dir == 0) { ch = sl; valid = sl < j; }
;       else { ch = (sl < 4) ? (3 - sl) : (71 - sl); valid = (j < 4) ? (sl < 4 && ch > j) : (sl < 4 || ch > j); }
;       ab[e] = valid ? ag[(size_t)ch * 1024] : mkf2(1.f, 0.f);
;     }
;     float A = 1.f, Bv = 0.f;
; #pragma unroll
;     for (int e = 0; e < 34; ++e) { A *= ab[e].x; Bv = ab[e].x * Bv + ab[e].y; }
;     ((f32x2*)carry)[(part * 2 + dir) * 64 + c] = mkf2(A, Bv);
	v_add_f32_e32 v3, v9, v3
	s_movk_i32 s3, 0x1040
	v_mad_u64_u32 v[34:35], s[4:5], v10, s3, v[2:3]
	s_movk_i32 s3, 0x900
	ds_write_b32 v34, v3 offset:9216
	v_cvt_pk_bf16_f32 v3, v3, s0
	v_mad_u64_u32 v[34:35], s[4:5], v10, s3, v[32:33]
	ds_write_b16 v34, v3
	v_mul_f32_e32 v3, v8, v15
	v_fmac_f32_e32 v3, v5, v11
	v_fmac_f32_e32 v3, v7, v13
	v_fmac_f32_e32 v3, v6, v18
	v_add_f32_e32 v12, v9, v3
	v_mad_u64_u32 v[2:3], s[4:5], v17, s54, v[2:3]
	v_cvt_pk_bf16_f32 v3, v12, s0
	v_mad_u64_u32 v[10:11], s[4:5], v17, s60, v[32:33]
	ds_write_b16 v10, v3
	v_mul_f32_e32 v3, v8, v13
	v_fmac_f32_e32 v3, v5, v15
	v_fmac_f32_e32 v3, v7, v18
	v_fmac_f32_e32 v3, v6, v16
	v_add_f32_e32 v3, v9, v3
	v_add_u32_e32 v11, 0x2400, v2
	ds_write2_b32 v11, v12, v3 offset1:65
	v_cvt_pk_bf16_f32 v3, v3, s0
	ds_write_b16 v10, v3 offset:144
	v_mul_f32_e32 v3, v8, v18
	v_fmac_f32_e32 v3, v5, v13
	v_fmac_f32_e32 v3, v7, v16
	v_fmac_f32_e32 v3, v6, v20
	v_add_f32_e32 v3, v9, v3
	v_cvt_pk_bf16_f32 v12, v3, s0
	ds_write_b16 v10, v12 offset:288
	v_mul_f32_e32 v12, v8, v16
	v_fmac_f32_e32 v12, v5, v18
	v_fmac_f32_e32 v12, v7, v20
	v_fmac_f32_e32 v12, v6, v19
	v_add_f32_e32 v12, v9, v12
	ds_write2_b32 v11, v3, v12 offset0:130 offset1:195
	v_cvt_pk_bf16_f32 v3, v12, s0
	ds_write_b16 v10, v3 offset:432
	v_mul_f32_e32 v3, v8, v20
	v_fmac_f32_e32 v3, v5, v16
	v_fmac_f32_e32 v3, v7, v19
	v_fmac_f32_e32 v3, v6, v22
	v_add_f32_e32 v3, v9, v3
	v_cvt_pk_bf16_f32 v11, v3, s0
	ds_write_b16 v10, v11 offset:576
	v_mul_f32_e32 v11, v8, v19
	v_fmac_f32_e32 v11, v5, v20
	v_fmac_f32_e32 v11, v7, v22
	v_fmac_f32_e32 v11, v6, v21
	v_add_f32_e32 v11, v9, v11
	v_add_u32_e32 v12, 0x2800, v2
	ds_write2_b32 v12, v3, v11 offset0:4 offset1:69
	v_cvt_pk_bf16_f32 v3, v11, s0
	ds_write_b16 v10, v3 offset:720
	v_mul_f32_e32 v3, v8, v22
	v_fmac_f32_e32 v3, v5, v19
	v_fmac_f32_e32 v3, v7, v21
	v_fmac_f32_e32 v3, v6, v24
	v_add_f32_e32 v3, v9, v3
	v_cvt_pk_bf16_f32 v11, v3, s0
	ds_write_b16 v10, v11 offset:864
	v_mul_f32_e32 v11, v8, v21
	v_fmac_f32_e32 v11, v5, v22
	v_fmac_f32_e32 v11, v7, v24
	v_fmac_f32_e32 v11, v6, v23
	v_add_f32_e32 v11, v9, v11
	ds_write2_b32 v12, v3, v11 offset0:134 offset1:199
	v_cvt_pk_bf16_f32 v3, v11, s0
	ds_write_b16 v10, v3 offset:1008
	v_mul_f32_e32 v3, v8, v24
	v_fmac_f32_e32 v3, v5, v21
	v_fmac_f32_e32 v3, v7, v23
	v_fmac_f32_e32 v3, v6, v26
	v_add_f32_e32 v3, v9, v3
	v_cvt_pk_bf16_f32 v11, v3, s0
	ds_write_b16 v10, v11 offset:1152
	v_mul_f32_e32 v11, v8, v23
	v_fmac_f32_e32 v11, v5, v24
	v_fmac_f32_e32 v11, v7, v26
	v_fmac_f32_e32 v11, v6, v25
	v_add_f32_e32 v11, v9, v11
	v_add_u32_e32 v12, 0x2c00, v2
	ds_write2_b32 v12, v3, v11 offset0:8 offset1:73
	v_cvt_pk_bf16_f32 v3, v11, s0
	ds_write_b16 v10, v3 offset:1296
	v_mul_f32_e32 v3, v8, v26
	v_fmac_f32_e32 v3, v5, v23
	v_fmac_f32_e32 v3, v7, v25
	v_fmac_f32_e32 v3, v6, v28
	v_add_f32_e32 v3, v9, v3
	v_cvt_pk_bf16_f32 v11, v3, s0
	ds_write_b16 v10, v11 offset:1440
	v_mul_f32_e32 v11, v8, v25
	v_fmac_f32_e32 v11, v5, v26
	v_fmac_f32_e32 v11, v7, v28
	v_fmac_f32_e32 v11, v6, v27
	v_add_f32_e32 v11, v9, v11
	ds_write2_b32 v12, v3, v11 offset0:138 offset1:203
	v_cvt_pk_bf16_f32 v3, v11, s0
	ds_write_b16 v10, v3 offset:1584
	v_mul_f32_e32 v3, v8, v28
	v_fmac_f32_e32 v3, v5, v25
	v_fmac_f32_e32 v3, v7, v27
	v_fmac_f32_e32 v3, v6, v30
	v_add_f32_e32 v3, v9, v3
	v_cvt_pk_bf16_f32 v11, v3, s0
	ds_write_b16 v10, v11 offset:1728
	v_mul_f32_e32 v11, v8, v27
	v_fmac_f32_e32 v11, v5, v28
	v_fmac_f32_e32 v11, v7, v30
	v_fmac_f32_e32 v11, v6, v29
	v_add_f32_e32 v11, v9, v11
	v_add_u32_e32 v12, 0x3000, v2
	ds_write2_b32 v12, v3, v11 offset0:12 offset1:77
	v_cvt_pk_bf16_f32 v3, v11, s0
	ds_write_b16 v10, v3 offset:1872
	v_mul_f32_e32 v3, v8, v30
	v_fmac_f32_e32 v3, v5, v27
	v_fmac_f32_e32 v3, v7, v29
	v_fmac_f32_e32 v3, v6, v14
	v_add_f32_e32 v3, v9, v3
	ds_write_b32 v2, v3 offset:12856
	v_cvt_pk_bf16_f32 v2, v3, s0
	ds_write_b16 v10, v2 offset:2016
	v_ashrrev_i32_e32 v78, 7, v76
	v_bfe_u32 v79, v76, 6, 1
	v_lshlrev_b32_e32 v75, 3, v4
	v_lshrrev_b32_e32 v74, 6, v76
	v_mov_b32_e32 v2, 1.0
	v_mov_b32_e32 v3, 0
	v_mov_b32_e32 v6, 1.0
	v_mov_b32_e32 v7, 0
	v_mov_b32_e32 v8, 1.0
	v_mov_b32_e32 v9, 0
	v_mov_b32_e32 v10, 1.0
	v_mov_b32_e32 v11, 0
	v_mov_b32_e32 v12, 1.0
	v_mov_b32_e32 v13, 0
	v_mov_b32_e32 v14, 1.0
	v_mov_b32_e32 v15, 0
	v_mov_b32_e32 v16, 1.0
	v_mov_b32_e32 v17, 0
	v_mov_b32_e32 v18, 1.0
	v_mov_b32_e32 v19, 0
	v_mov_b32_e32 v20, 1.0
	v_mov_b32_e32 v21, 0
	v_mov_b32_e32 v22, 1.0
	v_mov_b32_e32 v23, 0
	v_mov_b32_e32 v24, 1.0
	v_mov_b32_e32 v25, 0
	v_mov_b32_e32 v26, 1.0
	v_mov_b32_e32 v27, 0
	v_mov_b32_e32 v28, 1.0
	v_mov_b32_e32 v29, 0
	v_mov_b32_e32 v30, 1.0
	v_mov_b32_e32 v31, 0
	v_mov_b32_e32 v32, 1.0
	v_mov_b32_e32 v33, 0
	v_mov_b32_e32 v34, 1.0
	v_mov_b32_e32 v35, 0
	v_mov_b32_e32 v36, 1.0
	v_mov_b32_e32 v37, 0
	v_mov_b32_e32 v38, 1.0
	v_mov_b32_e32 v39, 0
	v_mov_b32_e32 v42, 1.0
	v_mov_b32_e32 v43, 0
	v_mov_b32_e32 v44, 1.0
	v_mov_b32_e32 v45, 0
	v_mov_b32_e32 v46, 1.0
	v_mov_b32_e32 v47, 0
	v_mov_b32_e32 v48, 1.0
	v_mov_b32_e32 v49, 0
	v_mov_b32_e32 v50, 1.0
	v_mov_b32_e32 v51, 0
	v_mov_b32_e32 v52, 1.0
	v_mov_b32_e32 v53, 0
	v_mov_b32_e32 v54, 1.0
	v_mov_b32_e32 v55, 0
	v_mov_b32_e32 v56, 1.0
	v_mov_b32_e32 v57, 0
	v_mov_b32_e32 v58, 1.0
	v_mov_b32_e32 v59, 0
	v_mov_b32_e32 v60, 1.0
	v_mov_b32_e32 v61, 0
	v_mov_b32_e32 v62, 1.0
	v_mov_b32_e32 v63, 0
	v_mov_b32_e32 v64, 1.0
	v_mov_b32_e32 v65, 0
	v_mov_b32_e32 v66, 1.0
	v_mov_b32_e32 v67, 0
	v_mov_b32_e32 v68, 1.0
	v_mov_b32_e32 v69, 0
	v_mov_b32_e32 v70, 1.0
	v_mov_b32_e32 v71, 0
	v_mov_b32_e32 v72, 1.0
	v_mov_b32_e32 v73, 0
	v_readfirstlane_b32 s9, v74
	s_and_b32 s10, s9, 1
	s_lshr_b32 s11, s9, 1
	s_mulk_i32 s2, 0x44
	s_ashr_i32 s3, s2, 31
	s_lshl_b64 s[2:3], s[2:3], 13
	s_add_u32 s2, s6, s2
	s_addc_u32 s3, s7, s3
	s_add_u32 s2, s2, 0xea7c000
	s_addc_u32 s3, s3, 0
	s_lshl_b32 s12, s10, 12
	s_add_u32 s2, s2, s12
	s_addc_u32 s3, s3, 0
	s_mul_i32 s13, s11, 34
	s_cmp_lt_i32 s34, 4
	s_cselect_b32 s12, 3, 0x47
	s_sub_i32 s12, s12, s34
	s_cmp_eq_u32 s10, 0
	s_cselect_b32 s8, s34, s12
	s_sub_i32 s8, s8, s13
	s_mov_b32 s23, 0xffffe000
	s_cmp_lt_i32 s13, 4
	s_cselect_b32 s12, 3, 0x47
	s_sub_i32 s12, s12, s13
	s_cmp_eq_u32 s10, 0
	s_cselect_b32 s12, s13, s12
	s_cselect_b32 s4, 0x2000, s23
	s_cselect_b32 s5, 0, -1
	s_lshl_b32 s12, s12, 13
	s_add_u32 s2, s2, s12
	s_addc_u32 s3, s3, 0
	s_xor_b32 s22, s11, 1
	s_and_b32 s22, s22, s10
	s_mul_i32 s22, s22, 0x88000
	s_cmp_le_i32 s8, 0
	s_cbranch_scc1 .Llru_carry_done
;     ...
;   if (pass == 3) {
;     const int part = tid >> 7, dir = (tid >> 6) & 1, c = tid & 63, cg = g * 64 + c;
;     const f32x2* ag = agg + ((size_t)(b * 68) * 2 + dir) * 512 + cg;
;     f32x2 ab[34];
; #pragma unroll
;     for (int e = 0; e < 34; ++e) {
;       const int sl = part * 34 + e;
;       int ch; bool valid;
;       if (dir == 0) { ch = sl; valid = sl < j; }
;       else { ch = (sl < 4) ? (3 - sl) : (71 - sl); valid = (j < 4) ? (sl < 4 && ch > j) : (sl < 4 || ch > j); }
;       ab[e] = valid ? ag[(size_t)ch * 1024] : mkf2(1.f, 0.f);
;     }
	global_load_dwordx2 v[2:3], v75, s[2:3]
	s_add_u32 s2, s2, s4
	s_addc_u32 s3, s3, s5
	s_cmp_le_i32 s8, 1
	s_cbranch_scc1 .Llru_carry_done
	global_load_dwordx2 v[6:7], v75, s[2:3]
	s_add_u32 s2, s2, s4
	s_addc_u32 s3, s3, s5
	s_cmp_le_i32 s8, 2
	s_cbranch_scc1 .Llru_carry_done
	global_load_dwordx2 v[8:9], v75, s[2:3]
	s_add_u32 s2, s2, s4
	s_addc_u32 s3, s3, s5
	s_cmp_le_i32 s8, 3
	s_cbranch_scc1 .Llru_carry_done
	global_load_dwordx2 v[10:11], v75, s[2:3]
	s_add_u32 s2, s2, s4
	s_addc_u32 s3, s3, s5
	s_add_u32 s2, s2, s22
	s_addc_u32 s3, s3, 0
	s_cmp_le_i32 s8, 4
	s_cbranch_scc1 .Llru_carry_done
	global_load_dwordx2 v[12:13], v75, s[2:3]
	s_add_u32 s2, s2, s4
	s_addc_u32 s3, s3, s5
	s_cmp_le_i32 s8, 5
	s_cbranch_scc1 .Llru_carry_done
	global_load_dwordx2 v[14:15], v75, s[2:3]
	s_add_u32 s2, s2, s4
	s_addc_u32 s3, s3, s5
	s_cmp_le_i32 s8, 6
	s_cbranch_scc1 .Llru_carry_done
	global_load_dwordx2 v[16:17], v75, s[2:3]
	s_add_u32 s2, s2, s4
	s_addc_u32 s3, s3, s5
	s_cmp_le_i32 s8, 7
	s_cbranch_scc1 .Llru_carry_done
	global_load_dwordx2 v[18:19], v75, s[2:3]
	s_add_u32 s2, s2, s4
	s_addc_u32 s3, s3, s5
	s_cmp_le_i32 s8, 8
	s_cbranch_scc1 .Llru_carry_done
	global_load_dwordx2 v[20:21], v75, s[2:3]
	s_add_u32 s2, s2, s4
	s_addc_u32 s3, s3, s5
	s_cmp_le_i32 s8, 9
	s_cbranch_scc1 .Llru_carry_done
	global_load_dwordx2 v[22:23], v75, s[2:3]
	s_add_u32 s2, s2, s4
	s_addc_u32 s3, s3, s5
	s_cmp_le_i32 s8, 10
	s_cbranch_scc1 .Llru_carry_done
	global_load_dwordx2 v[24:25], v75, s[2:3]
	s_add_u32 s2, s2, s4
	s_addc_u32 s3, s3, s5
	s_cmp_le_i32 s8, 11
	s_cbranch_scc1 .Llru_carry_done
	global_load_dwordx2 v[26:27], v75, s[2:3]
	s_add_u32 s2, s2, s4
	s_addc_u32 s3, s3, s5
	s_cmp_le_i32 s8, 12
	s_cbranch_scc1 .Llru_carry_done
	global_load_dwordx2 v[28:29], v75, s[2:3]
	s_add_u32 s2, s2, s4
	s_addc_u32 s3, s3, s5
	s_cmp_le_i32 s8, 13
	s_cbranch_scc1 .Llru_carry_done
	global_load_dwordx2 v[30:31], v75, s[2:3]
	s_add_u32 s2, s2, s4
	s_addc_u32 s3, s3, s5
	s_cmp_le_i32 s8, 14
	s_cbranch_scc1 .Llru_carry_done
	global_load_dwordx2 v[32:33], v75, s[2:3]
	s_add_u32 s2, s2, s4
	s_addc_u32 s3, s3, s5
	s_cmp_le_i32 s8, 15
	s_cbranch_scc1 .Llru_carry_done
	global_load_dwordx2 v[34:35], v75, s[2:3]
	s_add_u32 s2, s2, s4
	s_addc_u32 s3, s3, s5
	s_cmp_le_i32 s8, 16
	s_cbranch_scc1 .Llru_carry_done
	global_load_dwordx2 v[36:37], v75, s[2:3]
	s_add_u32 s2, s2, s4
	s_addc_u32 s3, s3, s5
	s_cmp_le_i32 s8, 17
	s_cbranch_scc1 .Llru_carry_done
	global_load_dwordx2 v[38:39], v75, s[2:3]
	s_add_u32 s2, s2, s4
	s_addc_u32 s3, s3, s5
	s_cmp_le_i32 s8, 18
	s_cbranch_scc1 .Llru_carry_done
	global_load_dwordx2 v[42:43], v75, s[2:3]
	s_add_u32 s2, s2, s4
	s_addc_u32 s3, s3, s5
	s_cmp_le_i32 s8, 19
	s_cbranch_scc1 .Llru_carry_done
	global_load_dwordx2 v[44:45], v75, s[2:3]
	s_add_u32 s2, s2, s4
	s_addc_u32 s3, s3, s5
	s_cmp_le_i32 s8, 20
	s_cbranch_scc1 .Llru_carry_done
	global_load_dwordx2 v[46:47], v75, s[2:3]
	s_add_u32 s2, s2, s4
	s_addc_u32 s3, s3, s5
	s_cmp_le_i32 s8, 21
	s_cbranch_scc1 .Llru_carry_done
	global_load_dwordx2 v[48:49], v75, s[2:3]
	s_add_u32 s2, s2, s4
	s_addc_u32 s3, s3, s5
	s_cmp_le_i32 s8, 22
	s_cbranch_scc1 .Llru_carry_done
	global_load_dwordx2 v[50:51], v75, s[2:3]
	s_add_u32 s2, s2, s4
	s_addc_u32 s3, s3, s5
	s_cmp_le_i32 s8, 23
	s_cbranch_scc1 .Llru_carry_done
	global_load_dwordx2 v[52:53], v75, s[2:3]
	s_add_u32 s2, s2, s4
	s_addc_u32 s3, s3, s5
	s_cmp_le_i32 s8, 24
	s_cbranch_scc1 .Llru_carry_done
	global_load_dwordx2 v[54:55], v75, s[2:3]
	s_add_u32 s2, s2, s4
	s_addc_u32 s3, s3, s5
	s_cmp_le_i32 s8, 25
	s_cbranch_scc1 .Llru_carry_done
	global_load_dwordx2 v[56:57], v75, s[2:3]
	s_add_u32 s2, s2, s4
	s_addc_u32 s3, s3, s5
	s_cmp_le_i32 s8, 26
	s_cbranch_scc1 .Llru_carry_done
	global_load_dwordx2 v[58:59], v75, s[2:3]
	s_add_u32 s2, s2, s4
	s_addc_u32 s3, s3, s5
	s_cmp_le_i32 s8, 27
	s_cbranch_scc1 .Llru_carry_done
	global_load_dwordx2 v[60:61], v75, s[2:3]
	s_add_u32 s2, s2, s4
	s_addc_u32 s3, s3, s5
	s_cmp_le_i32 s8, 28
	s_cbranch_scc1 .Llru_carry_done
	global_load_dwordx2 v[62:63], v75, s[2:3]
	s_add_u32 s2, s2, s4
	s_addc_u32 s3, s3, s5
	s_cmp_le_i32 s8, 29
	s_cbranch_scc1 .Llru_carry_done
	global_load_dwordx2 v[64:65], v75, s[2:3]
	s_add_u32 s2, s2, s4
	s_addc_u32 s3, s3, s5
	s_cmp_le_i32 s8, 30
	s_cbranch_scc1 .Llru_carry_done
	global_load_dwordx2 v[66:67], v75, s[2:3]
	s_add_u32 s2, s2, s4
	s_addc_u32 s3, s3, s5
	s_cmp_le_i32 s8, 31
	s_cbranch_scc1 .Llru_carry_done
	global_load_dwordx2 v[68:69], v75, s[2:3]
	s_add_u32 s2, s2, s4
	s_addc_u32 s3, s3, s5
	s_cmp_le_i32 s8, 32
	s_cbranch_scc1 .Llru_carry_done
	global_load_dwordx2 v[70:71], v75, s[2:3]
	s_add_u32 s2, s2, s4
	s_addc_u32 s3, s3, s5
	s_cmp_le_i32 s8, 33
	s_cbranch_scc1 .Llru_carry_done
	global_load_dwordx2 v[72:73], v75, s[2:3]
	s_add_u32 s2, s2, s4
	s_addc_u32 s3, s3, s5
;     ...
;     float A = 1.f, Bv = 0.f;
; #pragma unroll
;     for (int e = 0; e < 34; ++e) { A *= ab[e].x; Bv = ab[e].x * Bv + ab[e].y; }
;     ((f32x2*)carry)[(part * 2 + dir) * 64 + c] = mkf2(A, Bv);
;   }
;   __syncthreads();
;     ...
;   const u16* Wl = (const u16*)(p->ws + OFF_W) + W_LRU + (size_t)g * 256 * 64;
; #pragma unroll
;   for (int s = 0; s < 4; ++s) {
;     bf16x8 a = *(const bf16x8*)(Au + (th * 32 + l31) * 72 + s * 16 + hh * 8);
; #pragma unroll
;     for (int m = 0; m < 4; ++m) {
;       bf16x8 bb = *(const bf16x8*)(Wl + (size_t)(m * 64 + chh * 32 + l31) * 64 + s * 16 + hh * 8);
.Llru_carry_done:
	s_waitcnt vmcnt(0)
	v_mov_b32_e32 v41, v39
	v_fmac_f32_e32 v3, 0, v2
	v_fmac_f32_e32 v7, v3, v6
	v_fmac_f32_e32 v9, v7, v8
	v_fmac_f32_e32 v11, v9, v10
	v_fmac_f32_e32 v13, v11, v12
	v_fmac_f32_e32 v15, v13, v14
	v_fmac_f32_e32 v17, v15, v16
	v_fmac_f32_e32 v19, v17, v18
	v_fmac_f32_e32 v21, v19, v20
	v_fmac_f32_e32 v23, v21, v22
	v_fmac_f32_e32 v25, v23, v24
	v_fmac_f32_e32 v27, v25, v26
	v_fmac_f32_e32 v29, v27, v28
	v_fmac_f32_e32 v31, v29, v30
	v_fmac_f32_e32 v33, v31, v32
	v_fmac_f32_e32 v35, v33, v34
	v_fmac_f32_e32 v37, v35, v36
	v_mul_f32_e32 v40, v2, v6
	v_fmac_f32_e32 v41, v37, v38
	v_mov_b32_e32 v9, v42
	v_pk_mul_f32 v[2:3], v[40:41], v[8:9]
	v_pk_fma_f32 v[4:5], v[40:41], v[8:9], v[42:43]
	v_pk_mul_f32 v[2:3], v[2:3], v[10:11]
	v_mov_b32_e32 v13, v44
	v_mov_b32_e32 v4, v2
	v_pk_mul_f32 v[2:3], v[2:3], v[12:13]
	v_pk_fma_f32 v[4:5], v[4:5], v[12:13], v[44:45]
	v_pk_mul_f32 v[2:3], v[2:3], v[14:15]
	v_mov_b32_e32 v17, v46
	v_mov_b32_e32 v3, v5
	v_pk_mul_f32 v[4:5], v[2:3], v[16:17]
	v_pk_fma_f32 v[2:3], v[2:3], v[16:17], v[46:47]
	v_pk_mul_f32 v[4:5], v[4:5], v[18:19]
	v_mov_b32_e32 v21, v48
	v_mov_b32_e32 v2, v4
	v_pk_mul_f32 v[4:5], v[4:5], v[20:21]
	v_pk_fma_f32 v[2:3], v[2:3], v[20:21], v[48:49]
	v_pk_mul_f32 v[4:5], v[4:5], v[22:23]
	v_mov_b32_e32 v25, v50
	v_mov_b32_e32 v5, v3
	v_pk_mul_f32 v[2:3], v[4:5], v[24:25]
	v_pk_fma_f32 v[4:5], v[4:5], v[24:25], v[50:51]
	v_pk_mul_f32 v[2:3], v[2:3], v[26:27]
	v_mov_b32_e32 v29, v52
	v_mov_b32_e32 v4, v2
	v_pk_mul_f32 v[2:3], v[2:3], v[28:29]
	v_pk_fma_f32 v[4:5], v[4:5], v[28:29], v[52:53]
	v_pk_mul_f32 v[2:3], v[2:3], v[30:31]
	v_mov_b32_e32 v33, v54
	v_mov_b32_e32 v3, v5
	v_pk_mul_f32 v[4:5], v[2:3], v[32:33]
	v_pk_fma_f32 v[2:3], v[2:3], v[32:33], v[54:55]
	v_pk_mul_f32 v[4:5], v[4:5], v[34:35]
	v_mov_b32_e32 v37, v56
	v_lshlrev_b32_e32 v39, 9, v79
	v_mov_b32_e32 v2, v4
	v_pk_mul_f32 v[4:5], v[4:5], v[36:37]
	v_pk_fma_f32 v[2:3], v[2:3], v[36:37], v[56:57]
	v_pk_mul_f32 v[4:5], v[4:5], v[38:39]
	v_mov_b32_e32 v43, v58
	v_mov_b32_e32 v5, v3
	v_pk_mul_f32 v[2:3], v[4:5], v[42:43]
	v_pk_fma_f32 v[4:5], v[4:5], v[42:43], v[58:59]
	v_pk_mul_f32 v[2:3], v[2:3], v[44:45]
	v_mov_b32_e32 v47, v60
	v_mov_b32_e32 v4, v2
	v_pk_mul_f32 v[2:3], v[2:3], v[46:47]
	v_pk_fma_f32 v[4:5], v[4:5], v[46:47], v[60:61]
	v_pk_mul_f32 v[2:3], v[2:3], v[48:49]
	v_mov_b32_e32 v51, v62
	v_mov_b32_e32 v3, v5
	v_pk_mul_f32 v[4:5], v[2:3], v[50:51]
	v_pk_fma_f32 v[2:3], v[2:3], v[50:51], v[62:63]
	v_pk_mul_f32 v[4:5], v[4:5], v[52:53]
	v_mov_b32_e32 v55, v64
	v_mov_b32_e32 v2, v4
	v_pk_mul_f32 v[4:5], v[4:5], v[54:55]
	v_pk_fma_f32 v[2:3], v[2:3], v[54:55], v[64:65]
	v_pk_mul_f32 v[4:5], v[4:5], v[56:57]
	v_mov_b32_e32 v59, v66
	v_mov_b32_e32 v5, v3
	v_pk_mul_f32 v[2:3], v[4:5], v[58:59]
	v_pk_fma_f32 v[4:5], v[4:5], v[58:59], v[66:67]
	v_pk_mul_f32 v[2:3], v[2:3], v[60:61]
	v_mov_b32_e32 v63, v68
	v_mov_b32_e32 v4, v2
	v_pk_mul_f32 v[2:3], v[2:3], v[62:63]
	v_pk_fma_f32 v[4:5], v[4:5], v[62:63], v[68:69]
	v_pk_mul_f32 v[2:3], v[2:3], v[64:65]
	v_mov_b32_e32 v67, v70
	v_mov_b32_e32 v3, v5
	v_pk_mul_f32 v[4:5], v[2:3], v[66:67]
	v_pk_fma_f32 v[2:3], v[2:3], v[66:67], v[70:71]
	v_pk_mul_f32 v[4:5], v[4:5], v[68:69]
	v_mov_b32_e32 v71, v72
	v_mov_b32_e32 v2, v4
	v_pk_mul_f32 v[4:5], v[4:5], v[70:71]
	v_pk_fma_f32 v[2:3], v[2:3], v[70:71], v[72:73]
	v_and_b32_e32 v75, 0xffffff80, v76
	v_pk_mul_f32 v[4:5], v[4:5], v[72:73]
	v_lshl_or_b32 v2, v75, 3, v39
	v_and_b32_e32 v82, 31, v76
	v_lshrrev_b32_e32 v74, 5, v77
	v_mov_b32_e32 v5, v3
	v_lshl_add_u32 v2, v77, 3, v2
	s_lshl_b32 s2, s29, 15
	v_lshlrev_b32_e32 v77, 5, v78
	ds_write_b64 v2, v[4:5] offset:59136
	s_add_u32 s2, s6, s2
	v_or_b32_e32 v2, v77, v82
	v_lshlrev_b32_e32 v198, 4, v74
	s_addc_u32 s3, s7, 0
	v_mad_u64_u32 v[80:81], s[4:5], v2, s60, v[198:199]
	v_lshl_add_u64 v[90:91], s[2:3], 0, v[198:199]
	s_mov_b64 s[2:3], 0xe3e0000
	v_lshl_or_b32 v81, v79, 5, v82
	v_lshl_add_u64 v[10:11], v[90:91], 0, s[2:3]
	v_lshlrev_b32_e32 v12, 7, v81
	v_mov_b32_e32 v13, v199
	v_lshl_add_u64 v[72:73], v[10:11], 0, v[12:13]
	s_waitcnt lgkmcnt(0)
	s_barrier
; #define MFMA32(a, b, c) __builtin_amdgcn_mfma_f32_32x32x16_bf16((a), (b), (c), 0, 0, 0)
;     ...
; #pragma unroll
;   for (int s = 0; s < 4; ++s) {
;     bf16x8 a = *(const bf16x8*)(Au + (th * 32 + l31) * 72 + s * 16 + hh * 8);
; #pragma unroll
;     for (int m = 0; m < 4; ++m) {
;       bf16x8 bb = *(const bf16x8*)(Wl + (size_t)(m * 64 + chh * 32 + l31) * 64 + s * 16 + hh * 8);
;       acc[m] = MFMA32(a, bb, acc[m]);
;     }
;   }
;   asm volatile("s_nop 15\n\ts_nop 15" ::: "memory");
;   const int cl = chh * 32 + l31, cg = g * 64 + cl;
;   float hsum[16];
; #pragma unroll
;   for (int dir = 0; dir < 2; ++dir) {
;     const float ba = p->lru_ba[(l * 2 + dir) * 512 + cg], bx = p->lru_bx[(l * 2 + dir) * 512 + cg];
;     const float lam = p->lru_lam[(l * 2 + dir) * 512 + cg];
;     const float ex = __expf(-lam);
;     const float sp = (ex < 0.03f) ? ex * (1.f - ex * (0.5f - ex * (0.33333334f - 0.25f * ex))) : __logf(1.f + ex);
	global_load_dwordx4 v[2:5], v[72:73], off
	ds_read_b128 v[6:9], v80
	ds_read_b128 v[82:85], v80 offset:32
	v_or_b32_e32 v66, 0x2000, v12
	v_mov_b32_e32 v67, v199
	s_mov_b64 s[2:3], 0xe3e0020
	v_or_b32_e32 v68, 0x4000, v12
	v_mov_b32_e32 v69, v199
	v_lshl_add_u64 v[78:79], v[90:91], 0, s[2:3]
	v_or_b32_e32 v70, 0x6000, v12
	v_mov_b32_e32 v71, v199
	s_mov_b64 s[2:3], 0xe3e0040
	s_waitcnt vmcnt(0) lgkmcnt(1)
	v_mfma_f32_32x32x16_bf16 v[50:65], v[6:9], v[2:5], 0
	v_lshl_add_u64 v[2:3], v[10:11], 0, v[66:67]
	global_load_dwordx4 v[2:5], v[2:3], off
	s_nop 0
	global_load_dwordx4 v[86:89], v[72:73], off offset:32
	s_waitcnt vmcnt(1)
	v_mfma_f32_32x32x16_bf16 v[34:49], v[6:9], v[2:5], 0
	v_lshl_add_u64 v[2:3], v[10:11], 0, v[68:69]
	global_load_dwordx4 v[2:5], v[2:3], off
	s_waitcnt vmcnt(1) lgkmcnt(0)
	v_mfma_f32_32x32x16_bf16 v[50:65], v[82:85], v[86:89], v[50:65]
	v_lshl_add_u64 v[86:87], v[78:79], 0, v[66:67]
	global_load_dwordx4 v[86:89], v[86:87], off
	s_waitcnt vmcnt(0)
	v_mfma_f32_32x32x16_bf16 v[34:49], v[82:85], v[86:89], v[34:49]
	v_lshl_add_u64 v[86:87], v[78:79], 0, v[68:69]
	global_load_dwordx4 v[86:89], v[86:87], off
	v_lshl_add_u64 v[78:79], v[78:79], 0, v[70:71]
	v_mfma_f32_32x32x16_bf16 v[18:33], v[6:9], v[2:5], 0
	v_lshl_add_u64 v[2:3], v[10:11], 0, v[70:71]
	global_load_dwordx4 v[2:5], v[2:3], off
	s_waitcnt vmcnt(1)
	v_mfma_f32_32x32x16_bf16 v[18:33], v[82:85], v[86:89], v[18:33]
	global_load_dwordx4 v[86:89], v[78:79], off
	v_lshl_add_u64 v[78:79], v[90:91], 0, s[2:3]
	s_mov_b64 s[2:3], 0xe3e0060
	s_waitcnt vmcnt(1)
	v_mfma_f32_32x32x16_bf16 v[2:17], v[6:9], v[2:5], 0
	s_waitcnt vmcnt(0)
	v_mfma_f32_32x32x16_bf16 v[2:17], v[82:85], v[86:89], v[2:17]
	global_load_dwordx4 v[86:89], v[72:73], off offset:64
	ds_read_b128 v[82:85], v80 offset:64
	s_waitcnt vmcnt(0) lgkmcnt(0)
	v_mfma_f32_32x32x16_bf16 v[50:65], v[82:85], v[86:89], v[50:65]
	v_lshl_add_u64 v[86:87], v[78:79], 0, v[66:67]
	global_load_dwordx4 v[86:89], v[86:87], off
	s_waitcnt vmcnt(0)
	v_mfma_f32_32x32x16_bf16 v[34:49], v[82:85], v[86:89], v[34:49]
	v_lshl_add_u64 v[86:87], v[78:79], 0, v[68:69]
	global_load_dwordx4 v[86:89], v[86:87], off
	v_lshl_add_u64 v[78:79], v[78:79], 0, v[70:71]
	s_waitcnt vmcnt(0)
	v_mfma_f32_32x32x16_bf16 v[18:33], v[82:85], v[86:89], v[18:33]
	global_load_dwordx4 v[86:89], v[78:79], off
	v_lshl_add_u64 v[78:79], v[90:91], 0, s[2:3]
	v_lshl_add_u64 v[66:67], v[78:79], 0, v[66:67]
	s_waitcnt vmcnt(0)
	v_mfma_f32_32x32x16_bf16 v[2:17], v[82:85], v[86:89], v[2:17]
	global_load_dwordx4 v[86:89], v[72:73], off offset:96
	ds_read_b128 v[82:85], v80 offset:96
	v_or_b32_e32 v72, s28, v81
	s_waitcnt vmcnt(0) lgkmcnt(0)
	v_mfma_f32_32x32x16_bf16 v[50:65], v[82:85], v[86:89], v[50:65]
	global_load_dwordx4 v[86:89], v[66:67], off
	v_lshl_add_u64 v[66:67], v[78:79], 0, v[68:69]
	global_load_dwordx4 v[66:69], v[66:67], off
	s_waitcnt vmcnt(0)
	v_mfma_f32_32x32x16_bf16 v[18:33], v[82:85], v[66:69], v[18:33]
	v_lshl_add_u64 v[66:67], v[78:79], 0, v[70:71]
	global_load_dwordx4 v[66:69], v[66:67], off
	s_nop 15
	s_nop 15
	s_load_dwordx2 s[2:3], s[16:17], 0x80
	s_load_dwordx4 s[8:11], s[16:17], 0x90
	s_waitcnt vmcnt(0)
	v_mfma_f32_32x32x16_bf16 v[2:17], v[82:85], v[66:69], v[2:17]
	v_or_b32_e32 v66, s74, v72
	v_mov_b32_e32 v67, v199
	v_lshlrev_b64 v[70:71], 2, v[66:67]
	s_waitcnt lgkmcnt(0)
	v_lshl_add_u64 v[66:67], s[2:3], 0, v[70:71]
	v_lshl_add_u64 v[68:69], s[8:9], 0, v[70:71]
	v_lshl_add_u64 v[70:71], s[10:11], 0, v[70:71]
	global_load_dword v73, v[70:71], off
	global_load_dword v79, v[66:67], off
	global_load_dword v78, v[68:69], off
	v_mfma_f32_32x32x16_bf16 v[34:49], v[82:85], v[86:89], v[34:49]
	s_mov_b32 s2, 0x3cf5c28f
	s_waitcnt vmcnt(2)
	v_mul_f32_e32 v73, 0xbfb8aa3b, v73
	v_exp_f32_e32 v73, v73
	s_nop 0
	v_cmp_ngt_f32_e32 vcc, s2, v73
	s_and_saveexec_b64 s[2:3], vcc
	s_xor_b64 s[10:11], exec, s[2:3]
	s_cbranch_execz .LBB0_1514
	v_add_f32_e32 v73, 1.0, v73
	s_mov_b32 s2, 0x800000
	v_cmp_gt_f32_e32 vcc, s2, v73
	s_mov_b32 s2, 0x3f317217
	s_nop 0
	v_cndmask_b32_e64 v80, 0, 32, vcc
	v_ldexp_f32 v73, v73, v80
	v_log_f32_e32 v73, v73
	s_nop 0
	v_mul_f32_e32 v80, 0x3f317217, v73
	v_fma_f32 v80, v73, s2, -v80
	v_fmac_f32_e32 v80, 0x3377d1cf, v73
	s_mov_b32 s2, 0x7f800000
	v_fmac_f32_e32 v80, 0x3f317217, v73
	v_cmp_lt_f32_e64 s[8:9], |v73|, s2
	s_nop 1
	v_cndmask_b32_e64 v73, v73, v80, s[8:9]
	v_mov_b32_e32 v80, 0x41b17218
	v_cndmask_b32_e32 v80, 0, v80, vcc
	v_sub_f32_e32 v80, v73, v80
